# v124 variant: global-loop V LDS-DMA issued after QK MFMA 3 (K after 1) for more prefetch lead; placement unchanged
# speedup vs baseline: 1.0128x; 1.0128x over previous
.Lgo_mk:
	v_mfma_f32_32x32x16_bf16 v[80:95], v[136:139], v[100:103], v[80:95]
	v_add_f32_e32 v204, v204, v40
	v_add_f32_e32 v205, v205, v41
	v_add_f32_e32 v208, v208, v42
	v_add_f32_e32 v209, v209, v43
	v_cvt_pk_bf16_f32 v116, v40, v41
	v_cvt_pk_bf16_f32 v117, v42, v43
	v_mfma_f32_32x32x16_bf16 v[48:63], v[140:143], v[100:103], v[48:63]
	v_add_f32_e32 v204, v204, v44
	v_add_f32_e32 v205, v205, v45
	v_add_f32_e32 v208, v208, v46
	v_add_f32_e32 v209, v209, v47
	v_cvt_pk_bf16_f32 v118, v44, v45
	v_cvt_pk_bf16_f32 v119, v46, v47
	s_add_i32 s96, s7, 1
	s_cmp_lt_i32 s96, s71
	s_cbranch_scc0 .Lgo_mv
	s_mul_hi_u32 s80, s96, 0x55555556
	s_mul_i32 s80, s80, 3
	s_sub_u32 s80, s96, s80
	s_lshl_b32 s81, s80, 13
	s_cmp_eq_u32 s80, 2
	s_cselect_b32 s81, 0x6000, s81
	s_add_i32 s81, s81, 0x6000
	s_add_i32 s81, s81, s100
	s_mov_b32 m0, s81
	s_nop 0
	global_load_lds_dwordx4 v[246:247], off
	v_lshl_add_u64 v[246:247], v[246:247], 0, s[98:99]
.Lgo_mv:
	v_mfma_f32_32x32x16_bf16 v[80:95], v[144:147], v[104:107], v[80:95]
	v_add_f32_e32 v204, v204, v64
	v_add_f32_e32 v205, v205, v65
	v_add_f32_e32 v208, v208, v66
	v_add_f32_e32 v209, v209, v67
	v_cvt_pk_bf16_f32 v120, v64, v65
	v_cvt_pk_bf16_f32 v121, v66, v67
	v_mfma_f32_32x32x16_bf16 v[48:63], v[148:151], v[104:107], v[48:63]
	v_add_f32_e32 v204, v204, v68
	v_add_f32_e32 v205, v205, v69
	v_add_f32_e32 v208, v208, v70
	v_add_f32_e32 v209, v209, v71
	v_cvt_pk_bf16_f32 v122, v68, v69
	v_cvt_pk_bf16_f32 v123, v70, v71
	v_mfma_f32_32x32x16_bf16 v[80:95], v[152:155], v[108:111], v[80:95]
	v_add_f32_e32 v204, v204, v72
	v_add_f32_e32 v205, v205, v73
	v_add_f32_e32 v208, v208, v74
	v_add_f32_e32 v209, v209, v75
	v_cvt_pk_bf16_f32 v124, v72, v73
	v_cvt_pk_bf16_f32 v125, v74, v75
	v_mfma_f32_32x32x16_bf16 v[48:63], v[156:159], v[108:111], v[48:63]
	v_add_f32_e32 v204, v204, v76
	v_add_f32_e32 v205, v205, v77
	v_add_f32_e32 v208, v208, v78
	v_add_f32_e32 v209, v209, v79
	v_cvt_pk_bf16_f32 v126, v76, v77
	v_cvt_pk_bf16_f32 v127, v78, v79
	ds_read_b64_tr_b16 v[176:177], v242 offset:28672
	ds_read_b64_tr_b16 v[178:179], v242 offset:29184
	ds_read_b64_tr_b16 v[180:181], v242 offset:29696
	ds_read_b64_tr_b16 v[182:183], v242 offset:30208
	ds_read_b64_tr_b16 v[184:185], v242 offset:30720
	ds_read_b64_tr_b16 v[186:187], v242 offset:31232
	ds_read_b64_tr_b16 v[188:189], v242 offset:31744
	s_waitcnt lgkmcnt(14)
	ds_read_b64_tr_b16 v[190:191], v242 offset:32256
	s_waitcnt lgkmcnt(14)
	v_mfma_f32_32x32x16_bf16 v[0:15], v[160:163], v[112:115], v[0:15]
	v_exp_f32_e32 v80, v80
	v_exp_f32_e32 v81, v81
	v_exp_f32_e32 v82, v82
	v_exp_f32_e32 v83, v83
	s_waitcnt lgkmcnt(12)
	v_mfma_f32_32x32x16_bf16 v[0:15], v[164:167], v[116:119], v[0:15]
	v_exp_f32_e32 v84, v84
	v_exp_f32_e32 v85, v85
	v_exp_f32_e32 v86, v86
	v_exp_f32_e32 v87, v87
	s_waitcnt lgkmcnt(10)
	v_mfma_f32_32x32x16_bf16 v[0:15], v[168:171], v[120:123], v[0:15]
	v_exp_f32_e32 v88, v88
	v_exp_f32_e32 v89, v89
	v_exp_f32_e32 v90, v90
	v_exp_f32_e32 v91, v91
	ds_read_b128 v[128:131], v243
	ds_read_b128 v[132:135], v243 offset:512
	s_waitcnt lgkmcnt(10)
	v_mfma_f32_32x32x16_bf16 v[0:15], v[172:175], v[124:127], v[0:15]
	v_exp_f32_e32 v92, v92
	v_exp_f32_e32 v93, v93
	v_exp_f32_e32 v94, v94
	v_exp_f32_e32 v95, v95
	ds_read_b128 v[136:139], v243 offset:2048
	ds_read_b128 v[140:143], v243 offset:2560
	s_waitcnt lgkmcnt(10)
	v_mfma_f32_32x32x16_bf16 v[16:31], v[176:179], v[112:115], v[16:31]
	v_exp_f32_e32 v48, v48
	v_exp_f32_e32 v49, v49
	v_exp_f32_e32 v50, v50
	v_exp_f32_e32 v51, v51
	ds_read_b128 v[144:147], v243 offset:4096
	ds_read_b128 v[148:151], v243 offset:4608
	s_waitcnt lgkmcnt(10)
	v_mfma_f32_32x32x16_bf16 v[16:31], v[180:183], v[116:119], v[16:31]
	v_exp_f32_e32 v52, v52
	v_exp_f32_e32 v53, v53
	v_exp_f32_e32 v54, v54
	v_exp_f32_e32 v55, v55
	ds_read_b128 v[152:155], v243 offset:6144
	ds_read_b128 v[156:159], v243 offset:6656
	s_waitcnt lgkmcnt(10)
	v_mfma_f32_32x32x16_bf16 v[16:31], v[184:187], v[120:123], v[16:31]
	v_exp_f32_e32 v56, v56
	v_exp_f32_e32 v57, v57
	v_exp_f32_e32 v58, v58
	v_exp_f32_e32 v59, v59
	s_waitcnt lgkmcnt(8)
	v_mfma_f32_32x32x16_bf16 v[16:31], v[188:191], v[124:127], v[16:31]
	v_exp_f32_e32 v60, v60
	v_exp_f32_e32 v61, v61
	v_exp_f32_e32 v62, v62
	v_exp_f32_e32 v63, v63
	s_waitcnt lgkmcnt(0)
	s_and_b64 vcc, exec, s[82:83]
	s_cbranch_vccz .Lgo_w0
	s_waitcnt vmcnt(2)
	s_branch .Lgo_w1

.Lge_mk:
	v_mfma_f32_32x32x16_bf16 v[32:47], v[136:139], v[100:103], v[32:47]
	v_add_f32_e32 v204, v204, v88
	v_add_f32_e32 v205, v205, v89
	v_add_f32_e32 v208, v208, v90
	v_add_f32_e32 v209, v209, v91
	v_cvt_pk_bf16_f32 v116, v88, v89
	v_cvt_pk_bf16_f32 v117, v90, v91
	v_mfma_f32_32x32x16_bf16 v[64:79], v[140:143], v[100:103], v[64:79]
	v_add_f32_e32 v204, v204, v92
	v_add_f32_e32 v205, v205, v93
	v_add_f32_e32 v208, v208, v94
	v_add_f32_e32 v209, v209, v95
	v_cvt_pk_bf16_f32 v118, v92, v93
	v_cvt_pk_bf16_f32 v119, v94, v95
	s_add_i32 s96, s7, 1
	s_cmp_lt_i32 s96, s71
	s_cbranch_scc0 .Lge_mv
	s_mul_hi_u32 s80, s96, 0x55555556
	s_mul_i32 s80, s80, 3
	s_sub_u32 s80, s96, s80
	s_lshl_b32 s81, s80, 13
	s_cmp_eq_u32 s80, 2
	s_cselect_b32 s81, 0x6000, s81
	s_add_i32 s81, s81, 0x6000
	s_add_i32 s81, s81, s100
	s_mov_b32 m0, s81
	s_nop 0
	global_load_lds_dwordx4 v[246:247], off
	v_lshl_add_u64 v[246:247], v[246:247], 0, s[98:99]
.Lge_mv:
	v_mfma_f32_32x32x16_bf16 v[32:47], v[144:147], v[104:107], v[32:47]
	v_add_f32_e32 v204, v204, v48
	v_add_f32_e32 v205, v205, v49
	v_add_f32_e32 v208, v208, v50
	v_add_f32_e32 v209, v209, v51
	v_cvt_pk_bf16_f32 v120, v48, v49
	v_cvt_pk_bf16_f32 v121, v50, v51
	v_mfma_f32_32x32x16_bf16 v[64:79], v[148:151], v[104:107], v[64:79]
	v_add_f32_e32 v204, v204, v52
	v_add_f32_e32 v205, v205, v53
	v_add_f32_e32 v208, v208, v54
	v_add_f32_e32 v209, v209, v55
	v_cvt_pk_bf16_f32 v122, v52, v53
	v_cvt_pk_bf16_f32 v123, v54, v55
	v_mfma_f32_32x32x16_bf16 v[32:47], v[152:155], v[108:111], v[32:47]
	v_add_f32_e32 v204, v204, v56
	v_add_f32_e32 v205, v205, v57
	v_add_f32_e32 v208, v208, v58
	v_add_f32_e32 v209, v209, v59
	v_cvt_pk_bf16_f32 v124, v56, v57
	v_cvt_pk_bf16_f32 v125, v58, v59
	v_mfma_f32_32x32x16_bf16 v[64:79], v[156:159], v[108:111], v[64:79]
	v_add_f32_e32 v204, v204, v60
	v_add_f32_e32 v205, v205, v61
	v_add_f32_e32 v208, v208, v62
	v_add_f32_e32 v209, v209, v63
	v_cvt_pk_bf16_f32 v126, v60, v61
	v_cvt_pk_bf16_f32 v127, v62, v63
	ds_read_b64_tr_b16 v[176:177], v242 offset:28672
	ds_read_b64_tr_b16 v[178:179], v242 offset:29184
	ds_read_b64_tr_b16 v[180:181], v242 offset:29696
	ds_read_b64_tr_b16 v[182:183], v242 offset:30208
	ds_read_b64_tr_b16 v[184:185], v242 offset:30720
	ds_read_b64_tr_b16 v[186:187], v242 offset:31232
	ds_read_b64_tr_b16 v[188:189], v242 offset:31744
	s_waitcnt lgkmcnt(14)
	ds_read_b64_tr_b16 v[190:191], v242 offset:32256
	s_waitcnt lgkmcnt(14)
	v_mfma_f32_32x32x16_bf16 v[0:15], v[160:163], v[112:115], v[0:15]
	v_exp_f32_e32 v32, v32
	v_exp_f32_e32 v33, v33
	v_exp_f32_e32 v34, v34
	v_exp_f32_e32 v35, v35
	s_waitcnt lgkmcnt(12)
	v_mfma_f32_32x32x16_bf16 v[0:15], v[164:167], v[116:119], v[0:15]
	v_exp_f32_e32 v36, v36
	v_exp_f32_e32 v37, v37
	v_exp_f32_e32 v38, v38
	v_exp_f32_e32 v39, v39
	s_waitcnt lgkmcnt(10)
	v_mfma_f32_32x32x16_bf16 v[0:15], v[168:171], v[120:123], v[0:15]
	v_exp_f32_e32 v40, v40
	v_exp_f32_e32 v41, v41
	v_exp_f32_e32 v42, v42
	v_exp_f32_e32 v43, v43
	ds_read_b128 v[128:131], v243
	ds_read_b128 v[132:135], v243 offset:512
	s_waitcnt lgkmcnt(10)
	v_mfma_f32_32x32x16_bf16 v[0:15], v[172:175], v[124:127], v[0:15]
	v_exp_f32_e32 v44, v44
	v_exp_f32_e32 v45, v45
	v_exp_f32_e32 v46, v46
	v_exp_f32_e32 v47, v47
	ds_read_b128 v[136:139], v243 offset:2048
	ds_read_b128 v[140:143], v243 offset:2560
	s_waitcnt lgkmcnt(10)
	v_mfma_f32_32x32x16_bf16 v[16:31], v[176:179], v[112:115], v[16:31]
	v_exp_f32_e32 v64, v64
	v_exp_f32_e32 v65, v65
	v_exp_f32_e32 v66, v66
	v_exp_f32_e32 v67, v67
	ds_read_b128 v[144:147], v243 offset:4096
	ds_read_b128 v[148:151], v243 offset:4608
	s_waitcnt lgkmcnt(10)
	v_mfma_f32_32x32x16_bf16 v[16:31], v[180:183], v[116:119], v[16:31]
	v_exp_f32_e32 v68, v68
	v_exp_f32_e32 v69, v69
	v_exp_f32_e32 v70, v70
	v_exp_f32_e32 v71, v71
	ds_read_b128 v[152:155], v243 offset:6144
	ds_read_b128 v[156:159], v243 offset:6656
	s_waitcnt lgkmcnt(10)
	v_mfma_f32_32x32x16_bf16 v[16:31], v[184:187], v[120:123], v[16:31]
	v_exp_f32_e32 v72, v72
	v_exp_f32_e32 v73, v73
	v_exp_f32_e32 v74, v74
	v_exp_f32_e32 v75, v75
	s_waitcnt lgkmcnt(8)
	v_mfma_f32_32x32x16_bf16 v[16:31], v[188:191], v[124:127], v[16:31]
	v_exp_f32_e32 v76, v76
	v_exp_f32_e32 v77, v77
	v_exp_f32_e32 v78, v78
	v_exp_f32_e32 v79, v79
	s_waitcnt lgkmcnt(0)
	s_and_b64 vcc, exec, s[82:83]
	s_cbranch_vccz .Lge_w0
	s_waitcnt vmcnt(2)
	s_branch .Lge_w1
